# wave-uniform skip of the causal-mask block for waves that are entirely unmasked in a band tile (wid >= 2*jb+2), 4 band-loop sites
# speedup vs baseline: 1.0015x; 1.0015x over previous
.LBB0_425:
	s_add_i32 s16, s92, s50
	s_add_i32 s8, s90, s87
	s_add_i32 s9, s16, 2
	s_cmp_lt_i32 s9, 0
	s_mov_b32 s9, m0
	s_mov_b32 m0, s8
	s_nop 0
	global_load_lds_dwordx4 v[206:207], off
	s_mov_b32 m0, s9
	s_cbranch_scc1 .LBB0_427
	s_add_i32 s94, s16, 3
	s_lshl_b32 s94, s94, 1
	s_cmp_ge_u32 s84, s94
	s_cbranch_scc1 .LBB0_427
	v_add_u32_e32 v60, 0xffffffa5, v0
	v_add_u32_e32 v59, 0xffffff85, v0
	v_cmp_le_i32_e32 vcc, v60, v219
	s_nop 1
	v_cndmask_b32_e32 v98, v236, v98, vcc
	v_cmp_lt_i32_e32 vcc, v59, v219
	s_nop 1
	v_cndmask_b32_e32 v115, v236, v115, vcc
	v_cmp_le_i32_e32 vcc, v59, v219
	v_add_u32_e32 v59, 0xffffffa6, v0
	s_nop 0
	v_cndmask_b32_e32 v114, v236, v114, vcc
	v_cmp_le_i32_e32 vcc, v59, v219
	v_add_u32_e32 v59, 0xffffff87, v0
	s_nop 0
	v_cndmask_b32_e32 v99, v236, v99, vcc
	v_cmp_le_i32_e32 vcc, v59, v219
	v_add_u32_e32 v59, 0xffffffa7, v0
	s_nop 0
	v_cndmask_b32_e32 v116, v236, v116, vcc
	v_cmp_le_i32_e32 vcc, v59, v219
	v_add_u32_e32 v59, 0xffffff88, v0
	s_nop 0
	v_cndmask_b32_e32 v100, v236, v100, vcc
	v_cmp_le_i32_e32 vcc, v59, v219
	v_add_u32_e32 v59, 0xffffffa8, v0
	s_nop 0
	v_cndmask_b32_e32 v117, v236, v117, vcc
	v_cmp_le_i32_e32 vcc, v59, v219
	v_add_u32_e32 v59, 0xffffff8d, v0
	s_nop 0
	v_cndmask_b32_e32 v101, v236, v101, vcc
	v_cmp_le_i32_e32 vcc, v59, v219
	v_add_u32_e32 v59, 0xffffffad, v0
	s_nop 0
	v_cndmask_b32_e32 v118, v236, v118, vcc
	v_cmp_le_i32_e32 vcc, v59, v219
	v_add_u32_e32 v59, 0xffffff8e, v0
	s_nop 0
	v_cndmask_b32_e32 v102, v236, v102, vcc
	v_cmp_le_i32_e32 vcc, v59, v219
	v_add_u32_e32 v59, 0xffffffae, v0
	s_nop 0
	v_cndmask_b32_e32 v119, v236, v119, vcc
	v_cmp_le_i32_e32 vcc, v59, v219
	v_add_u32_e32 v59, 0xffffff8f, v0
	s_nop 0
	v_cndmask_b32_e32 v103, v236, v103, vcc
	v_cmp_le_i32_e32 vcc, v59, v219
	v_add_u32_e32 v59, 0xffffffaf, v0
	s_nop 0
	v_cndmask_b32_e32 v120, v236, v120, vcc
	v_cmp_le_i32_e32 vcc, v59, v219
	v_add_u32_e32 v59, 0xffffff90, v0
	s_nop 0
	v_cndmask_b32_e32 v104, v236, v104, vcc
	v_cmp_le_i32_e32 vcc, v59, v219
	v_add_u32_e32 v59, 0xffffffb0, v0
	s_nop 0
	v_cndmask_b32_e32 v121, v236, v121, vcc
	v_cmp_le_i32_e32 vcc, v59, v219
	v_add_u32_e32 v59, 0xffffff95, v0
	s_nop 0
	v_cndmask_b32_e32 v105, v236, v105, vcc
	v_cmp_le_i32_e32 vcc, v59, v219
	v_add_u32_e32 v59, 0xffffffb5, v0
	s_nop 0
	v_cndmask_b32_e32 v122, v236, v122, vcc
	v_cmp_le_i32_e32 vcc, v59, v219
	v_add_u32_e32 v59, 0xffffff96, v0
	s_nop 0
	v_cndmask_b32_e32 v106, v236, v106, vcc
	v_cmp_le_i32_e32 vcc, v59, v219
	v_add_u32_e32 v59, 0xffffffb6, v0
	s_nop 0
	v_cndmask_b32_e32 v123, v236, v123, vcc
	v_cmp_le_i32_e32 vcc, v59, v219
	v_add_u32_e32 v59, 0xffffff97, v0
	s_nop 0
	v_cndmask_b32_e32 v107, v236, v107, vcc
	v_cmp_le_i32_e32 vcc, v59, v219
	v_add_u32_e32 v59, 0xffffffb7, v0
	s_nop 0
	v_cndmask_b32_e32 v124, v236, v124, vcc
	v_cmp_le_i32_e32 vcc, v59, v219
	v_add_u32_e32 v59, 0xffffff98, v0
	s_nop 0
	v_cndmask_b32_e32 v108, v236, v108, vcc
	v_cmp_le_i32_e32 vcc, v59, v219
	v_add_u32_e32 v59, 0xffffffb8, v0
	s_nop 0
	v_cndmask_b32_e32 v125, v236, v125, vcc
	v_cmp_le_i32_e32 vcc, v59, v219
	v_add_u32_e32 v59, 0xffffff9d, v0
	s_nop 0
	v_cndmask_b32_e32 v109, v236, v109, vcc
	v_cmp_le_i32_e32 vcc, v59, v219
	v_add_u32_e32 v59, 0xffffffbd, v0
	s_nop 0
	v_cndmask_b32_e32 v126, v236, v126, vcc
	v_cmp_le_i32_e32 vcc, v59, v219
	v_add_u32_e32 v59, 0xffffff9e, v0
	s_nop 0
	v_cndmask_b32_e32 v110, v236, v110, vcc
	v_cmp_le_i32_e32 vcc, v59, v219
	v_add_u32_e32 v59, 0xffffffbe, v0
	s_nop 0
	v_cndmask_b32_e32 v127, v236, v127, vcc
	v_cmp_le_i32_e32 vcc, v59, v219
	v_add_u32_e32 v59, 0xffffff9f, v0
	s_nop 0
	v_cndmask_b32_e32 v111, v236, v111, vcc
	v_cmp_le_i32_e32 vcc, v59, v219
	v_add_u32_e32 v59, 0xffffffbf, v0
	s_nop 0
	v_cndmask_b32_e32 v128, v236, v128, vcc
	v_cmp_le_i32_e32 vcc, v59, v219
	v_add_u32_e32 v59, 0xffffffa0, v0
	s_nop 0
	v_cndmask_b32_e32 v112, v236, v112, vcc
	v_cmp_le_i32_e32 vcc, v59, v219
	v_subrev_u32_e32 v59, 64, v0
	s_nop 0
	v_cndmask_b32_e32 v129, v236, v129, vcc
	v_cmp_le_i32_e32 vcc, v59, v219
	s_nop 1
	v_cndmask_b32_e32 v113, v236, v113, vcc

.LBB0_442:
	s_add_i32 s16, s16, 3
	s_cmp_lt_i32 s16, 0
	s_cbranch_scc1 .LBB0_444
	s_add_i32 s94, s16, 1
	s_lshl_b32 s94, s94, 1
	s_cmp_ge_u32 s84, s94
	s_cbranch_scc1 .LBB0_444
	v_subrev_u32_e32 v98, 27, v0
	v_subrev_u32_e32 v81, 59, v0
	v_cmp_le_i32_e32 vcc, v98, v219
	s_nop 1
	v_cndmask_b32_e32 v50, v236, v50, vcc
	v_cmp_lt_i32_e32 vcc, v81, v219
	s_nop 1
	v_cndmask_b32_e32 v83, v236, v83, vcc
	v_cmp_le_i32_e32 vcc, v81, v219
	v_subrev_u32_e32 v81, 26, v0
	s_nop 0
	v_cndmask_b32_e32 v82, v236, v82, vcc
	v_cmp_le_i32_e32 vcc, v81, v219
	v_subrev_u32_e32 v81, 57, v0
	s_nop 0
	v_cndmask_b32_e32 v51, v236, v51, vcc
	v_cmp_le_i32_e32 vcc, v81, v219
	v_subrev_u32_e32 v81, 25, v0
	s_nop 0
	v_cndmask_b32_e32 v84, v236, v84, vcc
	v_cmp_le_i32_e32 vcc, v81, v219
	v_subrev_u32_e32 v81, 56, v0
	s_nop 0
	v_cndmask_b32_e32 v52, v236, v52, vcc
	v_cmp_le_i32_e32 vcc, v81, v219
	v_subrev_u32_e32 v81, 24, v0
	s_nop 0
	v_cndmask_b32_e32 v85, v236, v85, vcc
	v_cmp_le_i32_e32 vcc, v81, v219
	v_subrev_u32_e32 v81, 51, v0
	s_nop 0
	v_cndmask_b32_e32 v53, v236, v53, vcc
	v_cmp_le_i32_e32 vcc, v81, v219
	v_subrev_u32_e32 v81, 19, v0
	s_nop 0
	v_cndmask_b32_e32 v86, v236, v86, vcc
	v_cmp_le_i32_e32 vcc, v81, v219
	v_subrev_u32_e32 v81, 50, v0
	s_nop 0
	v_cndmask_b32_e32 v54, v236, v54, vcc
	v_cmp_le_i32_e32 vcc, v81, v219
	v_subrev_u32_e32 v81, 18, v0
	s_nop 0
	v_cndmask_b32_e32 v87, v236, v87, vcc
	v_cmp_le_i32_e32 vcc, v81, v219
	v_subrev_u32_e32 v81, 49, v0
	s_nop 0
	v_cndmask_b32_e32 v55, v236, v55, vcc
	v_cmp_le_i32_e32 vcc, v81, v219
	v_subrev_u32_e32 v81, 17, v0
	s_nop 0
	v_cndmask_b32_e32 v88, v236, v88, vcc
	v_cmp_le_i32_e32 vcc, v81, v219
	v_subrev_u32_e32 v81, 48, v0
	s_nop 0
	v_cndmask_b32_e32 v56, v236, v56, vcc
	v_cmp_le_i32_e32 vcc, v81, v219
	v_add_u32_e32 v81, -16, v0
	s_nop 0
	v_cndmask_b32_e32 v89, v236, v89, vcc
	v_cmp_le_i32_e32 vcc, v81, v219
	v_subrev_u32_e32 v81, 43, v0
	s_nop 0
	v_cndmask_b32_e32 v57, v236, v57, vcc
	v_cmp_le_i32_e32 vcc, v81, v219
	v_add_u32_e32 v81, -11, v0
	s_nop 0
	v_cndmask_b32_e32 v90, v236, v90, vcc
	v_cmp_le_i32_e32 vcc, v81, v219
	v_subrev_u32_e32 v81, 42, v0
	s_nop 0
	v_cndmask_b32_e32 v58, v236, v58, vcc
	v_cmp_le_i32_e32 vcc, v81, v219
	v_add_u32_e32 v81, -10, v0
	s_nop 0
	v_cndmask_b32_e32 v91, v236, v91, vcc
	v_cmp_le_i32_e32 vcc, v81, v219
	v_subrev_u32_e32 v81, 41, v0
	s_nop 0
	v_cndmask_b32_e32 v59, v236, v59, vcc
	v_cmp_le_i32_e32 vcc, v81, v219
	v_add_u32_e32 v81, -9, v0
	s_nop 0
	v_cndmask_b32_e32 v92, v236, v92, vcc
	v_cmp_le_i32_e32 vcc, v81, v219
	v_subrev_u32_e32 v81, 40, v0
	s_nop 0
	v_cndmask_b32_e32 v60, v236, v60, vcc
	v_cmp_le_i32_e32 vcc, v81, v219
	v_add_u32_e32 v81, -8, v0
	s_nop 0
	v_cndmask_b32_e32 v93, v236, v93, vcc
	v_cmp_le_i32_e32 vcc, v81, v219
	v_subrev_u32_e32 v81, 35, v0
	s_nop 0
	v_cndmask_b32_e32 v61, v236, v61, vcc
	v_cmp_le_i32_e32 vcc, v81, v219
	v_add_u32_e32 v81, -3, v0
	s_nop 0
	v_cndmask_b32_e32 v94, v236, v94, vcc
	v_cmp_le_i32_e32 vcc, v81, v219
	v_subrev_u32_e32 v81, 34, v0
	s_nop 0
	v_cndmask_b32_e32 v62, v236, v62, vcc
	v_cmp_le_i32_e32 vcc, v81, v219
	v_add_u32_e32 v81, -2, v0
	s_nop 0
	v_cndmask_b32_e32 v95, v236, v95, vcc
	v_cmp_le_i32_e32 vcc, v81, v219
	v_subrev_u32_e32 v81, 33, v0
	s_nop 0
	v_cndmask_b32_e32 v63, v236, v63, vcc
	v_cmp_le_i32_e32 vcc, v81, v219
	v_add_u32_e32 v81, -1, v0
	s_nop 0
	v_cndmask_b32_e32 v96, v236, v96, vcc
	v_cmp_le_i32_e32 vcc, v81, v219
	v_subrev_u32_e32 v81, 32, v0
	s_nop 0
	v_cndmask_b32_e32 v64, v236, v64, vcc
	v_cmp_le_i32_e32 vcc, v81, v219
	s_nop 1
	v_cndmask_b32_e32 v97, v236, v97, vcc
	v_cmp_le_i32_e32 vcc, v0, v219
	s_nop 1
	v_cndmask_b32_e32 v65, v236, v65, vcc

.LBB0_503:
	v_lshl_add_u64 v[14:15], v[226:227], 0, s[40:41]
	v_lshl_add_u64 v[98:99], v[14:15], 0, s[18:19]
	s_add_i32 s8, s87, s83
	s_mov_b32 s9, m0
	s_mov_b32 m0, s8
	s_nop 0
	global_load_lds_dwordx4 v[98:99], off
	s_mov_b32 m0, s9
	s_add_i32 s16, s89, s46
	v_lshl_add_u64 v[232:233], v[228:229], 0, s[40:41]
	s_add_i32 s8, s87, s84
	s_add_i32 s9, s16, 2
	v_lshl_add_u64 v[98:99], v[232:233], 0, s[18:19]
	s_cmp_lt_i32 s9, 0
	s_mov_b32 s9, m0
	s_mov_b32 m0, s8
	s_nop 0
	global_load_lds_dwordx4 v[98:99], off
	s_mov_b32 m0, s9
	s_cbranch_scc1 .LBB0_505
	s_add_i32 s94, s16, 3
	s_lshl_b32 s94, s94, 1
	s_cmp_ge_u32 s50, s94
	s_cbranch_scc1 .LBB0_505
	v_add_u32_e32 v98, 0xffffffa5, v0
	v_add_u32_e32 v97, 0xffffff85, v0
	v_cmp_le_i32_e32 vcc, v98, v246
	s_nop 1
	v_cndmask_b32_e32 v128, v236, v128, vcc
	v_cmp_lt_i32_e32 vcc, v97, v246
	s_nop 1
	v_cndmask_b32_e32 v145, v236, v145, vcc
	v_cmp_le_i32_e32 vcc, v97, v246
	v_add_u32_e32 v97, 0xffffffa6, v0
	s_nop 0
	v_cndmask_b32_e32 v144, v236, v144, vcc
	v_cmp_le_i32_e32 vcc, v97, v246
	v_add_u32_e32 v97, 0xffffff87, v0
	s_nop 0
	v_cndmask_b32_e32 v129, v236, v129, vcc
	v_cmp_le_i32_e32 vcc, v97, v246
	v_add_u32_e32 v97, 0xffffffa7, v0
	s_nop 0
	v_cndmask_b32_e32 v146, v236, v146, vcc
	v_cmp_le_i32_e32 vcc, v97, v246
	v_add_u32_e32 v97, 0xffffff88, v0
	s_nop 0
	v_cndmask_b32_e32 v130, v236, v130, vcc
	v_cmp_le_i32_e32 vcc, v97, v246
	v_add_u32_e32 v97, 0xffffffa8, v0
	s_nop 0
	v_cndmask_b32_e32 v147, v236, v147, vcc
	v_cmp_le_i32_e32 vcc, v97, v246
	v_add_u32_e32 v97, 0xffffff8d, v0
	s_nop 0
	v_cndmask_b32_e32 v131, v236, v131, vcc
	v_cmp_le_i32_e32 vcc, v97, v246
	v_add_u32_e32 v97, 0xffffffad, v0
	s_nop 0
	v_cndmask_b32_e32 v148, v236, v148, vcc
	v_cmp_le_i32_e32 vcc, v97, v246
	v_add_u32_e32 v97, 0xffffff8e, v0
	s_nop 0
	v_cndmask_b32_e32 v132, v236, v132, vcc
	v_cmp_le_i32_e32 vcc, v97, v246
	v_add_u32_e32 v97, 0xffffffae, v0
	s_nop 0
	v_cndmask_b32_e32 v149, v236, v149, vcc
	v_cmp_le_i32_e32 vcc, v97, v246
	v_add_u32_e32 v97, 0xffffff8f, v0
	s_nop 0
	v_cndmask_b32_e32 v133, v236, v133, vcc
	v_cmp_le_i32_e32 vcc, v97, v246
	v_add_u32_e32 v97, 0xffffffaf, v0
	s_nop 0
	v_cndmask_b32_e32 v150, v236, v150, vcc
	v_cmp_le_i32_e32 vcc, v97, v246
	v_add_u32_e32 v97, 0xffffff90, v0
	s_nop 0
	v_cndmask_b32_e32 v134, v236, v134, vcc
	v_cmp_le_i32_e32 vcc, v97, v246
	v_add_u32_e32 v97, 0xffffffb0, v0
	s_nop 0
	v_cndmask_b32_e32 v151, v236, v151, vcc
	v_cmp_le_i32_e32 vcc, v97, v246
	v_add_u32_e32 v97, 0xffffff95, v0
	s_nop 0
	v_cndmask_b32_e32 v135, v236, v135, vcc
	v_cmp_le_i32_e32 vcc, v97, v246
	v_add_u32_e32 v97, 0xffffffb5, v0
	s_nop 0
	v_cndmask_b32_e32 v152, v236, v152, vcc
	v_cmp_le_i32_e32 vcc, v97, v246
	v_add_u32_e32 v97, 0xffffff96, v0
	s_nop 0
	v_cndmask_b32_e32 v136, v236, v136, vcc
	v_cmp_le_i32_e32 vcc, v97, v246
	v_add_u32_e32 v97, 0xffffffb6, v0
	s_nop 0
	v_cndmask_b32_e32 v153, v236, v153, vcc
	v_cmp_le_i32_e32 vcc, v97, v246
	v_add_u32_e32 v97, 0xffffff97, v0
	s_nop 0
	v_cndmask_b32_e32 v137, v236, v137, vcc
	v_cmp_le_i32_e32 vcc, v97, v246
	v_add_u32_e32 v97, 0xffffffb7, v0
	s_nop 0
	v_cndmask_b32_e32 v154, v236, v154, vcc
	v_cmp_le_i32_e32 vcc, v97, v246
	v_add_u32_e32 v97, 0xffffff98, v0
	s_nop 0
	v_cndmask_b32_e32 v138, v236, v138, vcc
	v_cmp_le_i32_e32 vcc, v97, v246
	v_add_u32_e32 v97, 0xffffffb8, v0
	s_nop 0
	v_cndmask_b32_e32 v155, v236, v155, vcc
	v_cmp_le_i32_e32 vcc, v97, v246
	v_add_u32_e32 v97, 0xffffff9d, v0
	s_nop 0
	v_cndmask_b32_e32 v139, v236, v139, vcc
	v_cmp_le_i32_e32 vcc, v97, v246
	v_add_u32_e32 v97, 0xffffffbd, v0
	s_nop 0
	v_cndmask_b32_e32 v156, v236, v156, vcc
	v_cmp_le_i32_e32 vcc, v97, v246
	v_add_u32_e32 v97, 0xffffff9e, v0
	s_nop 0
	v_cndmask_b32_e32 v140, v236, v140, vcc
	v_cmp_le_i32_e32 vcc, v97, v246
	v_add_u32_e32 v97, 0xffffffbe, v0
	s_nop 0
	v_cndmask_b32_e32 v157, v236, v157, vcc
	v_cmp_le_i32_e32 vcc, v97, v246
	v_add_u32_e32 v97, 0xffffff9f, v0
	s_nop 0
	v_cndmask_b32_e32 v141, v236, v141, vcc
	v_cmp_le_i32_e32 vcc, v97, v246
	v_add_u32_e32 v97, 0xffffffbf, v0
	s_nop 0
	v_cndmask_b32_e32 v158, v236, v158, vcc
	v_cmp_le_i32_e32 vcc, v97, v246
	v_add_u32_e32 v97, 0xffffffa0, v0
	s_nop 0
	v_cndmask_b32_e32 v142, v236, v142, vcc
	v_cmp_le_i32_e32 vcc, v97, v246
	v_subrev_u32_e32 v97, 64, v0
	s_nop 0
	v_cndmask_b32_e32 v159, v236, v159, vcc
	v_cmp_le_i32_e32 vcc, v97, v246
	s_nop 1
	v_cndmask_b32_e32 v143, v236, v143, vcc

.LBB0_518:
	s_add_i32 s16, s16, 3
	s_cmp_lt_i32 s16, 0
	s_cbranch_scc1 .LBB0_520
	s_add_i32 s94, s16, 1
	s_lshl_b32 s94, s94, 1
	s_cmp_ge_u32 s50, s94
	s_cbranch_scc1 .LBB0_520
	v_subrev_u32_e32 v15, 27, v0
	v_subrev_u32_e32 v14, 59, v0
	v_cmp_le_i32_e32 vcc, v15, v246
	s_nop 1
	v_cndmask_b32_e32 v96, v236, v96, vcc
	v_cmp_lt_i32_e32 vcc, v14, v246
	s_nop 1
	v_cndmask_b32_e32 v113, v236, v113, vcc
	v_cmp_le_i32_e32 vcc, v14, v246
	v_subrev_u32_e32 v14, 26, v0
	s_nop 0
	v_cndmask_b32_e32 v112, v236, v112, vcc
	v_cmp_le_i32_e32 vcc, v14, v246
	v_subrev_u32_e32 v14, 57, v0
	s_nop 0
	v_cndmask_b32_e32 v97, v236, v97, vcc
	v_cmp_le_i32_e32 vcc, v14, v246
	v_subrev_u32_e32 v14, 25, v0
	s_nop 0
	v_cndmask_b32_e32 v114, v236, v114, vcc
	v_cmp_le_i32_e32 vcc, v14, v246
	v_subrev_u32_e32 v14, 56, v0
	s_nop 0
	v_cndmask_b32_e32 v98, v236, v98, vcc
	v_cmp_le_i32_e32 vcc, v14, v246
	v_subrev_u32_e32 v14, 24, v0
	s_nop 0
	v_cndmask_b32_e32 v115, v236, v115, vcc
	v_cmp_le_i32_e32 vcc, v14, v246
	v_subrev_u32_e32 v14, 51, v0
	s_nop 0
	v_cndmask_b32_e32 v99, v236, v99, vcc
	v_cmp_le_i32_e32 vcc, v14, v246
	v_subrev_u32_e32 v14, 19, v0
	s_nop 0
	v_cndmask_b32_e32 v116, v236, v116, vcc
	v_cmp_le_i32_e32 vcc, v14, v246
	v_subrev_u32_e32 v14, 50, v0
	s_nop 0
	v_cndmask_b32_e32 v100, v236, v100, vcc
	v_cmp_le_i32_e32 vcc, v14, v246
	v_subrev_u32_e32 v14, 18, v0
	s_nop 0
	v_cndmask_b32_e32 v117, v236, v117, vcc
	v_cmp_le_i32_e32 vcc, v14, v246
	v_subrev_u32_e32 v14, 49, v0
	s_nop 0
	v_cndmask_b32_e32 v101, v236, v101, vcc
	v_cmp_le_i32_e32 vcc, v14, v246
	v_subrev_u32_e32 v14, 17, v0
	s_nop 0
	v_cndmask_b32_e32 v118, v236, v118, vcc
	v_cmp_le_i32_e32 vcc, v14, v246
	v_subrev_u32_e32 v14, 48, v0
	s_nop 0
	v_cndmask_b32_e32 v102, v236, v102, vcc
	v_cmp_le_i32_e32 vcc, v14, v246
	v_add_u32_e32 v14, -16, v0
	s_nop 0
	v_cndmask_b32_e32 v119, v236, v119, vcc
	v_cmp_le_i32_e32 vcc, v14, v246
	v_subrev_u32_e32 v14, 43, v0
	s_nop 0
	v_cndmask_b32_e32 v103, v236, v103, vcc
	v_cmp_le_i32_e32 vcc, v14, v246
	v_add_u32_e32 v14, -11, v0
	s_nop 0
	v_cndmask_b32_e32 v120, v236, v120, vcc
	v_cmp_le_i32_e32 vcc, v14, v246
	v_subrev_u32_e32 v14, 42, v0
	s_nop 0
	v_cndmask_b32_e32 v104, v236, v104, vcc
	v_cmp_le_i32_e32 vcc, v14, v246
	v_add_u32_e32 v14, -10, v0
	s_nop 0
	v_cndmask_b32_e32 v121, v236, v121, vcc
	v_cmp_le_i32_e32 vcc, v14, v246
	v_subrev_u32_e32 v14, 41, v0
	s_nop 0
	v_cndmask_b32_e32 v105, v236, v105, vcc
	v_cmp_le_i32_e32 vcc, v14, v246
	v_add_u32_e32 v14, -9, v0
	s_nop 0
	v_cndmask_b32_e32 v122, v236, v122, vcc
	v_cmp_le_i32_e32 vcc, v14, v246
	v_subrev_u32_e32 v14, 40, v0
	s_nop 0
	v_cndmask_b32_e32 v106, v236, v106, vcc
	v_cmp_le_i32_e32 vcc, v14, v246
	v_add_u32_e32 v14, -8, v0
	s_nop 0
	v_cndmask_b32_e32 v123, v236, v123, vcc
	v_cmp_le_i32_e32 vcc, v14, v246
	v_subrev_u32_e32 v14, 35, v0
	s_nop 0
	v_cndmask_b32_e32 v107, v236, v107, vcc
	v_cmp_le_i32_e32 vcc, v14, v246
	v_add_u32_e32 v14, -3, v0
	s_nop 0
	v_cndmask_b32_e32 v124, v236, v124, vcc
	v_cmp_le_i32_e32 vcc, v14, v246
	v_subrev_u32_e32 v14, 34, v0
	s_nop 0
	v_cndmask_b32_e32 v108, v236, v108, vcc
	v_cmp_le_i32_e32 vcc, v14, v246
	v_add_u32_e32 v14, -2, v0
	s_nop 0
	v_cndmask_b32_e32 v125, v236, v125, vcc
	v_cmp_le_i32_e32 vcc, v14, v246
	v_subrev_u32_e32 v14, 33, v0
	s_nop 0
	v_cndmask_b32_e32 v109, v236, v109, vcc
	v_cmp_le_i32_e32 vcc, v14, v246
	v_add_u32_e32 v14, -1, v0
	s_nop 0
	v_cndmask_b32_e32 v126, v236, v126, vcc
	v_cmp_le_i32_e32 vcc, v14, v246
	v_subrev_u32_e32 v14, 32, v0
	s_nop 0
	v_cndmask_b32_e32 v110, v236, v110, vcc
	v_cmp_le_i32_e32 vcc, v14, v246
	s_nop 1
	v_cndmask_b32_e32 v127, v236, v127, vcc
	v_cmp_le_i32_e32 vcc, v0, v246
	s_nop 1
	v_cndmask_b32_e32 v111, v236, v111, vcc
